# phase-1 RMSNorm software pipelined: g in registers, two rows per half-trip with interleaved reductions, next pair of rows prefetched
# baseline (speedup 1.0000x reference)
; DI int tid_() { int t = threadIdx.x; asm volatile("" : "+v"(t)); return t; }
; DI unsigned pk2(float lo, float hi) { f32x2 v = {lo, hi}; bf16x2_t r = __builtin_convertvector(v, bf16x2_t); return __builtin_bit_cast(unsigned, r); }
; DI void phase_rmsnorm(const float* X, const float* g, bf16_t* H) {
;     const int lane = tid_() & 63, wave = __builtin_amdgcn_readfirstlane(tid_() >> 6);
;     for (int row = blockIdx.x * 4 + wave; row < NTOK; row += gridDim.x * 4) {
;         const float* xr = X + (size_t)row * DM;
;         f32x4 v[4]; float ss = 0.f;
; #pragma unroll
;         for (int i = 0; i < 4; ++i) { v[i] = *(const f32x4*)(xr + i * 256 + lane * 4); ss += v[i][0] * v[i][0] + v[i][1] * v[i][1] + v[i][2] * v[i][2] + v[i][3] * v[i][3]; }
; #pragma unroll
;         for (int o = 32; o >= 1; o >>= 1) ss += __shfl_xor(ss, o);
;         const float r = rsqrtf(ss * (1.f / DM) + 1e-6f);
; #pragma unroll
;         for (int i = 0; i < 4; ++i) {
;             const f32x4 gg = *(const f32x4*)(g + i * 256 + lane * 4);
;             u32x2 o2; o2[0] = pk2(v[i][0] * r * gg[0], v[i][1] * r * gg[1]); o2[1] = pk2(v[i][2] * r * gg[2], v[i][3] * r * gg[3]);
.LBB0_139:
	v_mov_b32_e32 v2, v210
	v_mov_b32_e32 v1, v210
	s_lshl_b32 s1, s2, 2
	v_readfirstlane_b32 s0, v1
	s_ashr_i32 s0, s0, 6
	s_add_i32 s0, s0, s1
	s_cmpk_gt_i32 s0, 0x7fff
	v_mbcnt_lo_u32_b32 v1, -1, 0
	s_cbranch_scc1 .LBB0_142
	v_lshlrev_b32_e32 v2, 2, v2
	v_and_b32_e32 v8, 0xfc, v2
	v_readlane_b32 s8, v251, 18
	v_mbcnt_hi_u32_b32 v13, -1, v1
	v_lshlrev_b32_e32 v6, 2, v8
	v_mov_b32_e32 v7, 0
	v_readlane_b32 s9, v251, 19
	v_readlane_b32 s10, v251, 20
	v_readlane_b32 s11, v251, 21
	v_and_b32_e32 v4, 64, v13
	v_lshl_add_u64 v[2:3], s[8:9], 0, v[6:7]
	v_add_u32_e32 v14, 64, v4
	v_lshl_add_u64 v[4:5], s[10:11], 0, v[6:7]
	v_lshrrev_b32_e32 v6, 5, v8
	v_lshlrev_b32_e32 v6, 21, v6
	v_and_b32_e32 v36, 0x1c, v8
	v_lshl_or_b32 v6, v36, 1, v6
	s_mov_b32 s98, 0x1000000
	s_mov_b32 s99, 0
	v_xor_b32_e32 v8, 32, v13
	v_cmp_lt_i32_e32 vcc, v8, v14
	v_xor_b32_e32 v9, 16, v13
	v_xor_b32_e32 v10, 8, v13
	v_cndmask_b32_e32 v8, v13, v8, vcc
	v_cmp_lt_i32_e32 vcc, v9, v14
	v_xor_b32_e32 v11, 4, v13
	v_xor_b32_e32 v12, 2, v13
	v_cndmask_b32_e32 v9, v13, v9, vcc
	v_cmp_lt_i32_e32 vcc, v10, v14
	v_xor_b32_e32 v15, 1, v13
	v_lshl_add_u64 v[6:7], s[78:79], 0, v[6:7]
	v_cndmask_b32_e32 v10, v13, v10, vcc
	v_cmp_lt_i32_e32 vcc, v11, v14
	s_lshl_b32 s6, s42, 2
	v_lshlrev_b32_e32 v8, 2, v8
	v_cndmask_b32_e32 v11, v13, v11, vcc
	v_cmp_lt_i32_e32 vcc, v12, v14
	v_lshlrev_b32_e32 v9, 2, v9
	v_lshlrev_b32_e32 v10, 2, v10
	v_cndmask_b32_e32 v12, v13, v12, vcc
	v_cmp_lt_i32_e32 vcc, v15, v14
	v_lshlrev_b32_e32 v11, 2, v11
	v_lshlrev_b32_e32 v12, 2, v12
	v_cndmask_b32_e32 v13, v13, v15, vcc
	v_lshlrev_b32_e32 v13, 2, v13
	v_mov_b32_e32 v14, 0x358637bd
	s_mov_b32 s7, 0x800000
	v_readlane_b32 s12, v251, 22
	v_readlane_b32 s13, v251, 23
	v_readlane_b32 s14, v251, 24
	v_readlane_b32 s15, v251, 25
	v_readlane_b32 s16, v251, 26
	v_readlane_b32 s17, v251, 27
	v_readlane_b32 s18, v251, 28
	v_readlane_b32 s19, v251, 29
	v_readlane_b32 s20, v251, 30
	v_readlane_b32 s21, v251, 31
	v_readlane_b32 s22, v251, 32
	v_readlane_b32 s23, v251, 33
	global_load_dwordx4 v[60:63], v[4:5], off
	global_load_dwordx4 v[64:67], v[4:5], off offset:1024
	global_load_dwordx4 v[68:71], v[4:5], off offset:2048
	global_load_dwordx4 v[72:75], v[4:5], off offset:3072
	s_mov_b32 s100, s0
	s_waitcnt vmcnt(0)
	s_cmp_lt_i32 s0, 0x8000
	s_cselect_b32 s8, s0, s100
	s_lshl_b32 s8, s8, 12
	s_mov_b32 s9, 0
	v_lshl_add_u64 v[184:185], v[2:3], 0, s[8:9]
	global_load_dwordx4 v[76:79], v[184:185], off
	global_load_dwordx4 v[80:83], v[184:185], off offset:1024
	global_load_dwordx4 v[84:87], v[184:185], off offset:2048
	global_load_dwordx4 v[88:91], v[184:185], off offset:3072
	s_add_i32 s1, s0, s6
	s_cmp_lt_i32 s1, 0x8000
	s_cselect_b32 s8, s1, s100
	s_lshl_b32 s8, s8, 12
	s_mov_b32 s9, 0
	v_lshl_add_u64 v[184:185], v[2:3], 0, s[8:9]
	global_load_dwordx4 v[92:95], v[184:185], off
	global_load_dwordx4 v[96:99], v[184:185], off offset:1024
	global_load_dwordx4 v[100:103], v[184:185], off offset:2048
	global_load_dwordx4 v[104:107], v[184:185], off offset:3072
	s_add_i32 s101, s0, s6
	s_add_i32 s101, s101, s6
	s_cmp_lt_i32 s101, 0x8000
	s_cselect_b32 s8, s101, s100
	s_lshl_b32 s8, s8, 12
	s_mov_b32 s9, 0
	v_lshl_add_u64 v[184:185], v[2:3], 0, s[8:9]
	global_load_dwordx4 v[108:111], v[184:185], off
	global_load_dwordx4 v[112:115], v[184:185], off offset:1024
	global_load_dwordx4 v[116:119], v[184:185], off offset:2048
	global_load_dwordx4 v[120:123], v[184:185], off offset:3072
	s_add_i32 s1, s101, s6
	s_cmp_lt_i32 s1, 0x8000
	s_cselect_b32 s8, s1, s100
	s_lshl_b32 s8, s8, 12
	s_mov_b32 s9, 0
	v_lshl_add_u64 v[184:185], v[2:3], 0, s[8:9]
	global_load_dwordx4 v[124:127], v[184:185], off
	global_load_dwordx4 v[128:131], v[184:185], off offset:1024
	global_load_dwordx4 v[132:135], v[184:185], off offset:2048
	global_load_dwordx4 v[136:139], v[184:185], off offset:3072
	s_cmp_lt_i32 s0, 0x8000
	s_cbranch_scc0 .Lrms_done
	s_waitcnt vmcnt(8)
	v_mov_b32_e32 v142, v77
	v_mov_b32_e32 v143, v81
	v_mov_b32_e32 v140, v76
	v_mov_b32_e32 v141, v80
	v_mov_b32_e32 v150, v85
	v_mov_b32_e32 v151, v89
	v_pk_mul_f32 v[142:143], v[142:143], v[142:143]
	v_mov_b32_e32 v144, v78
	v_mov_b32_e32 v145, v82
	v_mov_b32_e32 v148, v84
	v_mov_b32_e32 v149, v88
	v_pk_mul_f32 v[150:151], v[150:151], v[150:151]
	v_pk_fma_f32 v[140:141], v[140:141], v[140:141], v[142:143]
	v_mov_b32_e32 v146, v79
	v_mov_b32_e32 v147, v83
	v_mov_b32_e32 v152, v86
	v_mov_b32_e32 v153, v90
	v_pk_fma_f32 v[142:143], v[148:149], v[148:149], v[150:151]
	v_pk_fma_f32 v[140:141], v[144:145], v[144:145], v[140:141]
	v_mov_b32_e32 v154, v87
	v_mov_b32_e32 v155, v91
	v_pk_fma_f32 v[142:143], v[152:153], v[152:153], v[142:143]
	v_pk_fma_f32 v[140:141], v[146:147], v[146:147], v[140:141]
	v_pk_fma_f32 v[142:143], v[154:155], v[154:155], v[142:143]
	v_add_f32_e32 v156, v140, v141
	v_add_f32_e32 v156, v156, v142
	v_add_f32_e32 v156, v156, v143
	v_mov_b32_e32 v164, v93
	v_mov_b32_e32 v165, v97
	v_mov_b32_e32 v162, v92
	v_mov_b32_e32 v163, v96
	v_mov_b32_e32 v172, v101
	v_mov_b32_e32 v173, v105
	v_pk_mul_f32 v[164:165], v[164:165], v[164:165]
	v_mov_b32_e32 v166, v94
	v_mov_b32_e32 v167, v98
	v_mov_b32_e32 v170, v100
	v_mov_b32_e32 v171, v104
	v_pk_mul_f32 v[172:173], v[172:173], v[172:173]
	v_pk_fma_f32 v[162:163], v[162:163], v[162:163], v[164:165]
	v_mov_b32_e32 v168, v95
	v_mov_b32_e32 v169, v99
	v_mov_b32_e32 v174, v102
	v_mov_b32_e32 v175, v106
	v_pk_fma_f32 v[164:165], v[170:171], v[170:171], v[172:173]
	v_pk_fma_f32 v[162:163], v[166:167], v[166:167], v[162:163]
	v_mov_b32_e32 v176, v103
	v_mov_b32_e32 v177, v107
	v_pk_fma_f32 v[164:165], v[174:175], v[174:175], v[164:165]
	v_pk_fma_f32 v[162:163], v[168:169], v[168:169], v[162:163]
	v_pk_fma_f32 v[164:165], v[176:177], v[176:177], v[164:165]
	v_add_f32_e32 v178, v162, v163
	v_add_f32_e32 v178, v178, v164
	v_add_f32_e32 v178, v178, v165
	ds_bpermute_b32 v157, v8, v156
	ds_bpermute_b32 v179, v8, v178
	s_waitcnt lgkmcnt(1)
; DI unsigned pk2(float lo, float hi) { f32x2 v = {lo, hi}; bf16x2_t r = __builtin_convertvector(v, bf16x2_t); return __builtin_bit_cast(unsigned, r); }
; DI void phase_rmsnorm(const float* X, const float* g, bf16_t* H) {
;     ...
;         for (int i = 0; i < 4; ++i) { v[i] = *(const f32x4*)(xr + i * 256 + lane * 4); ss += v[i][0] * v[i][0] + v[i][1] * v[i][1] + v[i][2] * v[i][2] + v[i][3] * v[i][3]; }
; #pragma unroll
;         for (int o = 32; o >= 1; o >>= 1) ss += __shfl_xor(ss, o);
;         const float r = rsqrtf(ss * (1.f / DM) + 1e-6f);
; #pragma unroll
;         for (int i = 0; i < 4; ++i) {
;             const f32x4 gg = *(const f32x4*)(g + i * 256 + lane * 4);
;             u32x2 o2; o2[0] = pk2(v[i][0] * r * gg[0], v[i][1] * r * gg[1]); o2[1] = pk2(v[i][2] * r * gg[2], v[i][3] * r * gg[3]);
;             *(u32x2*)(H + (size_t)row * DM + i * 256 + lane * 4) = o2;
;         }
	v_add_f32_e32 v156, v156, v157
	s_waitcnt lgkmcnt(0)
	v_add_f32_e32 v178, v178, v179
	ds_bpermute_b32 v157, v9, v156
	ds_bpermute_b32 v179, v9, v178
	s_waitcnt lgkmcnt(1)
	v_add_f32_e32 v156, v156, v157
	s_waitcnt lgkmcnt(0)
	v_add_f32_e32 v178, v178, v179
	ds_bpermute_b32 v157, v10, v156
	ds_bpermute_b32 v179, v10, v178
	s_waitcnt lgkmcnt(1)
	v_add_f32_e32 v156, v156, v157
	s_waitcnt lgkmcnt(0)
	v_add_f32_e32 v178, v178, v179
	ds_bpermute_b32 v157, v11, v156
	ds_bpermute_b32 v179, v11, v178
	s_waitcnt lgkmcnt(1)
	v_add_f32_e32 v156, v156, v157
	s_waitcnt lgkmcnt(0)
	v_add_f32_e32 v178, v178, v179
	ds_bpermute_b32 v157, v12, v156
	ds_bpermute_b32 v179, v12, v178
	s_waitcnt lgkmcnt(1)
	v_add_f32_e32 v156, v156, v157
	s_waitcnt lgkmcnt(0)
	v_add_f32_e32 v178, v178, v179
	ds_bpermute_b32 v157, v13, v156
	ds_bpermute_b32 v179, v13, v178
	s_waitcnt lgkmcnt(1)
	v_add_f32_e32 v156, v156, v157
	s_waitcnt lgkmcnt(0)
	v_add_f32_e32 v178, v178, v179
	s_cmp_lt_i32 s0, 0x8000
	s_cselect_b32 s8, s0, s100
	s_lshl_b32 s8, s8, 6
	s_mov_b32 s9, 0
	v_fmamk_f32 v156, v156, 0x3a800000, v14
	v_mul_f32_e32 v157, 0x4b800000, v156
	v_cmp_gt_f32_e32 vcc, s7, v156
	s_nop 1
	v_cndmask_b32_e32 v156, v156, v157, vcc
	v_rsq_f32_e32 v156, v156
	v_lshl_add_u64 v[160:161], v[6:7], 0, s[8:9]
	v_mul_f32_e32 v158, 0x45800000, v156
	v_cndmask_b32_e32 v158, v156, v158, vcc
	v_pk_mul_f32 v[76:77], v[76:77], v[158:159] op_sel_hi:[1,0]
	v_pk_mul_f32 v[78:79], v[78:79], v[158:159] op_sel_hi:[1,0]
	v_pk_mul_f32 v[76:77], v[60:61], v[76:77]
	v_pk_mul_f32 v[78:79], v[62:63], v[78:79]
	v_cvt_pk_bf16_f32 v76, v76, v77
	v_cvt_pk_bf16_f32 v77, v78, v79
	global_store_dwordx2 v[160:161], v[76:77], off
	v_pk_mul_f32 v[80:81], v[80:81], v[158:159] op_sel_hi:[1,0]
	v_pk_mul_f32 v[82:83], v[82:83], v[158:159] op_sel_hi:[1,0]
	v_pk_mul_f32 v[80:81], v[64:65], v[80:81]
	v_pk_mul_f32 v[82:83], v[66:67], v[82:83]
	v_cvt_pk_bf16_f32 v80, v80, v81
	v_cvt_pk_bf16_f32 v81, v82, v83
	v_lshl_add_u64 v[160:161], v[160:161], 0, s[98:99]
	global_store_dwordx2 v[160:161], v[80:81], off
	v_pk_mul_f32 v[84:85], v[84:85], v[158:159] op_sel_hi:[1,0]
	v_pk_mul_f32 v[86:87], v[86:87], v[158:159] op_sel_hi:[1,0]
	v_pk_mul_f32 v[84:85], v[68:69], v[84:85]
	v_pk_mul_f32 v[86:87], v[70:71], v[86:87]
	v_cvt_pk_bf16_f32 v84, v84, v85
	v_cvt_pk_bf16_f32 v85, v86, v87
	v_lshl_add_u64 v[160:161], v[160:161], 0, s[98:99]
	global_store_dwordx2 v[160:161], v[84:85], off
	v_pk_mul_f32 v[88:89], v[88:89], v[158:159] op_sel_hi:[1,0]
	v_pk_mul_f32 v[90:91], v[90:91], v[158:159] op_sel_hi:[1,0]
	v_pk_mul_f32 v[88:89], v[72:73], v[88:89]
	v_pk_mul_f32 v[90:91], v[74:75], v[90:91]
	v_cvt_pk_bf16_f32 v88, v88, v89
	v_cvt_pk_bf16_f32 v89, v90, v91
	v_lshl_add_u64 v[160:161], v[160:161], 0, s[98:99]
	global_store_dwordx2 v[160:161], v[88:89], off
	s_add_i32 s101, s0, s6
	s_cmp_lt_i32 s101, 0x8000
	s_cselect_b32 s8, s101, s100
	s_lshl_b32 s8, s8, 6
	s_mov_b32 s9, 0
	v_fmamk_f32 v178, v178, 0x3a800000, v14
	v_mul_f32_e32 v179, 0x4b800000, v178
	v_cmp_gt_f32_e32 vcc, s7, v178
	s_nop 1
	v_cndmask_b32_e32 v178, v178, v179, vcc
	v_rsq_f32_e32 v178, v178
	v_lshl_add_u64 v[182:183], v[6:7], 0, s[8:9]
	v_mul_f32_e32 v180, 0x45800000, v178
	v_cndmask_b32_e32 v180, v178, v180, vcc
	v_pk_mul_f32 v[92:93], v[92:93], v[180:181] op_sel_hi:[1,0]
	v_pk_mul_f32 v[94:95], v[94:95], v[180:181] op_sel_hi:[1,0]
	v_pk_mul_f32 v[92:93], v[60:61], v[92:93]
	v_pk_mul_f32 v[94:95], v[62:63], v[94:95]
	v_cvt_pk_bf16_f32 v92, v92, v93
	v_cvt_pk_bf16_f32 v93, v94, v95
	global_store_dwordx2 v[182:183], v[92:93], off
	v_pk_mul_f32 v[96:97], v[96:97], v[180:181] op_sel_hi:[1,0]
	v_pk_mul_f32 v[98:99], v[98:99], v[180:181] op_sel_hi:[1,0]
	v_pk_mul_f32 v[96:97], v[64:65], v[96:97]
	v_pk_mul_f32 v[98:99], v[66:67], v[98:99]
	v_cvt_pk_bf16_f32 v96, v96, v97
	v_cvt_pk_bf16_f32 v97, v98, v99
	v_lshl_add_u64 v[182:183], v[182:183], 0, s[98:99]
	global_store_dwordx2 v[182:183], v[96:97], off
	v_pk_mul_f32 v[100:101], v[100:101], v[180:181] op_sel_hi:[1,0]
	v_pk_mul_f32 v[102:103], v[102:103], v[180:181] op_sel_hi:[1,0]
	v_pk_mul_f32 v[100:101], v[68:69], v[100:101]
	v_pk_mul_f32 v[102:103], v[70:71], v[102:103]
	v_cvt_pk_bf16_f32 v100, v100, v101
	v_cvt_pk_bf16_f32 v101, v102, v103
	v_lshl_add_u64 v[182:183], v[182:183], 0, s[98:99]
	global_store_dwordx2 v[182:183], v[100:101], off
	v_pk_mul_f32 v[104:105], v[104:105], v[180:181] op_sel_hi:[1,0]
	v_pk_mul_f32 v[106:107], v[106:107], v[180:181] op_sel_hi:[1,0]
	v_pk_mul_f32 v[104:105], v[72:73], v[104:105]
	v_pk_mul_f32 v[106:107], v[74:75], v[106:107]
	v_cvt_pk_bf16_f32 v104, v104, v105
	v_cvt_pk_bf16_f32 v105, v106, v107
	v_lshl_add_u64 v[182:183], v[182:183], 0, s[98:99]
	global_store_dwordx2 v[182:183], v[104:105], off
	s_add_i32 s0, s101, s6
	s_add_i32 s101, s0, s6
	s_add_i32 s101, s101, s6
	s_cmp_lt_i32 s101, 0x8000
	s_cselect_b32 s8, s101, s100
	s_lshl_b32 s8, s8, 12
	s_mov_b32 s9, 0
	v_lshl_add_u64 v[184:185], v[2:3], 0, s[8:9]
	global_load_dwordx4 v[76:79], v[184:185], off
	global_load_dwordx4 v[80:83], v[184:185], off offset:1024
	global_load_dwordx4 v[84:87], v[184:185], off offset:2048
	global_load_dwordx4 v[88:91], v[184:185], off offset:3072
	s_add_i32 s1, s101, s6
	s_cmp_lt_i32 s1, 0x8000
	s_cselect_b32 s8, s1, s100
	s_lshl_b32 s8, s8, 12
	s_mov_b32 s9, 0
	v_lshl_add_u64 v[184:185], v[2:3], 0, s[8:9]
	global_load_dwordx4 v[92:95], v[184:185], off
	global_load_dwordx4 v[96:99], v[184:185], off offset:1024
	global_load_dwordx4 v[100:103], v[184:185], off offset:2048
	global_load_dwordx4 v[104:107], v[184:185], off offset:3072
; DI unsigned pk2(float lo, float hi) { f32x2 v = {lo, hi}; bf16x2_t r = __builtin_convertvector(v, bf16x2_t); return __builtin_bit_cast(unsigned, r); }
; DI void phase_rmsnorm(const float* X, const float* g, bf16_t* H) {
;     ...
;     for (int row = blockIdx.x * 4 + wave; row < NTOK; row += gridDim.x * 4) {
;         const float* xr = X + (size_t)row * DM;
;         f32x4 v[4]; float ss = 0.f;
; #pragma unroll
;         for (int i = 0; i < 4; ++i) { v[i] = *(const f32x4*)(xr + i * 256 + lane * 4); ss += v[i][0] * v[i][0] + v[i][1] * v[i][1] + v[i][2] * v[i][2] + v[i][3] * v[i][3]; }
; #pragma unroll
;         for (int o = 32; o >= 1; o >>= 1) ss += __shfl_xor(ss, o);
;         const float r = rsqrtf(ss * (1.f / DM) + 1e-6f);
; #pragma unroll
;         for (int i = 0; i < 4; ++i) {
;             const f32x4 gg = *(const f32x4*)(g + i * 256 + lane * 4);
;             u32x2 o2; o2[0] = pk2(v[i][0] * r * gg[0], v[i][1] * r * gg[1]); o2[1] = pk2(v[i][2] * r * gg[2], v[i][3] * r * gg[3]);
;             *(u32x2*)(H + (size_t)row * DM + i * 256 + lane * 4) = o2;
;         }
.Lrms_loop:
	s_cmp_lt_i32 s0, 0x8000
	s_cbranch_scc0 .Lrms_done
	s_waitcnt vmcnt(16)
	v_mov_b32_e32 v142, v109
	v_mov_b32_e32 v143, v113
	v_mov_b32_e32 v140, v108
	v_mov_b32_e32 v141, v112
	v_mov_b32_e32 v150, v117
	v_mov_b32_e32 v151, v121
	v_pk_mul_f32 v[142:143], v[142:143], v[142:143]
	v_mov_b32_e32 v144, v110
	v_mov_b32_e32 v145, v114
	v_mov_b32_e32 v148, v116
	v_mov_b32_e32 v149, v120
	v_pk_mul_f32 v[150:151], v[150:151], v[150:151]
	v_pk_fma_f32 v[140:141], v[140:141], v[140:141], v[142:143]
	v_mov_b32_e32 v146, v111
	v_mov_b32_e32 v147, v115
	v_mov_b32_e32 v152, v118
	v_mov_b32_e32 v153, v122
	v_pk_fma_f32 v[142:143], v[148:149], v[148:149], v[150:151]
	v_pk_fma_f32 v[140:141], v[144:145], v[144:145], v[140:141]
	v_mov_b32_e32 v154, v119
	v_mov_b32_e32 v155, v123
	v_pk_fma_f32 v[142:143], v[152:153], v[152:153], v[142:143]
	v_pk_fma_f32 v[140:141], v[146:147], v[146:147], v[140:141]
	v_pk_fma_f32 v[142:143], v[154:155], v[154:155], v[142:143]
	v_add_f32_e32 v156, v140, v141
	v_add_f32_e32 v156, v156, v142
	v_add_f32_e32 v156, v156, v143
	v_mov_b32_e32 v164, v125
	v_mov_b32_e32 v165, v129
	v_mov_b32_e32 v162, v124
	v_mov_b32_e32 v163, v128
	v_mov_b32_e32 v172, v133
	v_mov_b32_e32 v173, v137
	v_pk_mul_f32 v[164:165], v[164:165], v[164:165]
	v_mov_b32_e32 v166, v126
	v_mov_b32_e32 v167, v130
	v_mov_b32_e32 v170, v132
	v_mov_b32_e32 v171, v136
	v_pk_mul_f32 v[172:173], v[172:173], v[172:173]
	v_pk_fma_f32 v[162:163], v[162:163], v[162:163], v[164:165]
	v_mov_b32_e32 v168, v127
	v_mov_b32_e32 v169, v131
	v_mov_b32_e32 v174, v134
	v_mov_b32_e32 v175, v138
	v_pk_fma_f32 v[164:165], v[170:171], v[170:171], v[172:173]
	v_pk_fma_f32 v[162:163], v[166:167], v[166:167], v[162:163]
	v_mov_b32_e32 v176, v135
	v_mov_b32_e32 v177, v139
	v_pk_fma_f32 v[164:165], v[174:175], v[174:175], v[164:165]
	v_pk_fma_f32 v[162:163], v[168:169], v[168:169], v[162:163]
	v_pk_fma_f32 v[164:165], v[176:177], v[176:177], v[164:165]
	v_add_f32_e32 v178, v162, v163
	v_add_f32_e32 v178, v178, v164
	v_add_f32_e32 v178, v178, v165
	ds_bpermute_b32 v157, v8, v156
	ds_bpermute_b32 v179, v8, v178
	s_waitcnt lgkmcnt(1)
	v_add_f32_e32 v156, v156, v157
	s_waitcnt lgkmcnt(0)
	v_add_f32_e32 v178, v178, v179
	ds_bpermute_b32 v157, v9, v156
	ds_bpermute_b32 v179, v9, v178
	s_waitcnt lgkmcnt(1)
	v_add_f32_e32 v156, v156, v157
	s_waitcnt lgkmcnt(0)
	v_add_f32_e32 v178, v178, v179
	ds_bpermute_b32 v157, v10, v156
	ds_bpermute_b32 v179, v10, v178
	s_waitcnt lgkmcnt(1)
	v_add_f32_e32 v156, v156, v157
	s_waitcnt lgkmcnt(0)
	v_add_f32_e32 v178, v178, v179
	ds_bpermute_b32 v157, v11, v156
	ds_bpermute_b32 v179, v11, v178
	s_waitcnt lgkmcnt(1)
	v_add_f32_e32 v156, v156, v157
	s_waitcnt lgkmcnt(0)
	v_add_f32_e32 v178, v178, v179
	ds_bpermute_b32 v157, v12, v156
	ds_bpermute_b32 v179, v12, v178
	s_waitcnt lgkmcnt(1)
	v_add_f32_e32 v156, v156, v157
	s_waitcnt lgkmcnt(0)
	v_add_f32_e32 v178, v178, v179
	ds_bpermute_b32 v157, v13, v156
	ds_bpermute_b32 v179, v13, v178
	s_waitcnt lgkmcnt(1)
	v_add_f32_e32 v156, v156, v157
	s_waitcnt lgkmcnt(0)
	v_add_f32_e32 v178, v178, v179
	s_cmp_lt_i32 s0, 0x8000
	s_cselect_b32 s8, s0, s100
	s_lshl_b32 s8, s8, 6
	s_mov_b32 s9, 0
	v_fmamk_f32 v156, v156, 0x3a800000, v14
	v_mul_f32_e32 v157, 0x4b800000, v156
	v_cmp_gt_f32_e32 vcc, s7, v156
	s_nop 1
	v_cndmask_b32_e32 v156, v156, v157, vcc
	v_rsq_f32_e32 v156, v156
	v_lshl_add_u64 v[160:161], v[6:7], 0, s[8:9]
	v_mul_f32_e32 v158, 0x45800000, v156
	v_cndmask_b32_e32 v158, v156, v158, vcc
	v_pk_mul_f32 v[108:109], v[108:109], v[158:159] op_sel_hi:[1,0]
	v_pk_mul_f32 v[110:111], v[110:111], v[158:159] op_sel_hi:[1,0]
	v_pk_mul_f32 v[108:109], v[60:61], v[108:109]
	v_pk_mul_f32 v[110:111], v[62:63], v[110:111]
	v_cvt_pk_bf16_f32 v108, v108, v109
	v_cvt_pk_bf16_f32 v109, v110, v111
	global_store_dwordx2 v[160:161], v[108:109], off
	v_pk_mul_f32 v[112:113], v[112:113], v[158:159] op_sel_hi:[1,0]
	v_pk_mul_f32 v[114:115], v[114:115], v[158:159] op_sel_hi:[1,0]
	v_pk_mul_f32 v[112:113], v[64:65], v[112:113]
	v_pk_mul_f32 v[114:115], v[66:67], v[114:115]
	v_cvt_pk_bf16_f32 v112, v112, v113
	v_cvt_pk_bf16_f32 v113, v114, v115
	v_lshl_add_u64 v[160:161], v[160:161], 0, s[98:99]
	global_store_dwordx2 v[160:161], v[112:113], off
	v_pk_mul_f32 v[116:117], v[116:117], v[158:159] op_sel_hi:[1,0]
	v_pk_mul_f32 v[118:119], v[118:119], v[158:159] op_sel_hi:[1,0]
	v_pk_mul_f32 v[116:117], v[68:69], v[116:117]
	v_pk_mul_f32 v[118:119], v[70:71], v[118:119]
	v_cvt_pk_bf16_f32 v116, v116, v117
	v_cvt_pk_bf16_f32 v117, v118, v119
	v_lshl_add_u64 v[160:161], v[160:161], 0, s[98:99]
	global_store_dwordx2 v[160:161], v[116:117], off
	v_pk_mul_f32 v[120:121], v[120:121], v[158:159] op_sel_hi:[1,0]
	v_pk_mul_f32 v[122:123], v[122:123], v[158:159] op_sel_hi:[1,0]
	v_pk_mul_f32 v[120:121], v[72:73], v[120:121]
	v_pk_mul_f32 v[122:123], v[74:75], v[122:123]
	v_cvt_pk_bf16_f32 v120, v120, v121
	v_cvt_pk_bf16_f32 v121, v122, v123
	v_lshl_add_u64 v[160:161], v[160:161], 0, s[98:99]
	global_store_dwordx2 v[160:161], v[120:121], off
	s_add_i32 s101, s0, s6
	s_cmp_lt_i32 s101, 0x8000
	s_cselect_b32 s8, s101, s100
	s_lshl_b32 s8, s8, 6
	s_mov_b32 s9, 0
	v_fmamk_f32 v178, v178, 0x3a800000, v14
	v_mul_f32_e32 v179, 0x4b800000, v178
	v_cmp_gt_f32_e32 vcc, s7, v178
	s_nop 1
	v_cndmask_b32_e32 v178, v178, v179, vcc
	v_rsq_f32_e32 v178, v178
	v_lshl_add_u64 v[182:183], v[6:7], 0, s[8:9]
	v_mul_f32_e32 v180, 0x45800000, v178
	v_cndmask_b32_e32 v180, v178, v180, vcc
	v_pk_mul_f32 v[124:125], v[124:125], v[180:181] op_sel_hi:[1,0]
	v_pk_mul_f32 v[126:127], v[126:127], v[180:181] op_sel_hi:[1,0]
	v_pk_mul_f32 v[124:125], v[60:61], v[124:125]
; DI unsigned pk2(float lo, float hi) { f32x2 v = {lo, hi}; bf16x2_t r = __builtin_convertvector(v, bf16x2_t); return __builtin_bit_cast(unsigned, r); }
; DI void phase_rmsnorm(const float* X, const float* g, bf16_t* H) {
;     ...
;         for (int i = 0; i < 4; ++i) { v[i] = *(const f32x4*)(xr + i * 256 + lane * 4); ss += v[i][0] * v[i][0] + v[i][1] * v[i][1] + v[i][2] * v[i][2] + v[i][3] * v[i][3]; }
; #pragma unroll
;         for (int o = 32; o >= 1; o >>= 1) ss += __shfl_xor(ss, o);
;         const float r = rsqrtf(ss * (1.f / DM) + 1e-6f);
; #pragma unroll
;         for (int i = 0; i < 4; ++i) {
;             const f32x4 gg = *(const f32x4*)(g + i * 256 + lane * 4);
;             u32x2 o2; o2[0] = pk2(v[i][0] * r * gg[0], v[i][1] * r * gg[1]); o2[1] = pk2(v[i][2] * r * gg[2], v[i][3] * r * gg[3]);
;             *(u32x2*)(H + (size_t)row * DM + i * 256 + lane * 4) = o2;
;         }
	v_pk_mul_f32 v[126:127], v[62:63], v[126:127]
	v_cvt_pk_bf16_f32 v124, v124, v125
	v_cvt_pk_bf16_f32 v125, v126, v127
	global_store_dwordx2 v[182:183], v[124:125], off
	v_pk_mul_f32 v[128:129], v[128:129], v[180:181] op_sel_hi:[1,0]
	v_pk_mul_f32 v[130:131], v[130:131], v[180:181] op_sel_hi:[1,0]
	v_pk_mul_f32 v[128:129], v[64:65], v[128:129]
	v_pk_mul_f32 v[130:131], v[66:67], v[130:131]
	v_cvt_pk_bf16_f32 v128, v128, v129
	v_cvt_pk_bf16_f32 v129, v130, v131
	v_lshl_add_u64 v[182:183], v[182:183], 0, s[98:99]
	global_store_dwordx2 v[182:183], v[128:129], off
	v_pk_mul_f32 v[132:133], v[132:133], v[180:181] op_sel_hi:[1,0]
	v_pk_mul_f32 v[134:135], v[134:135], v[180:181] op_sel_hi:[1,0]
	v_pk_mul_f32 v[132:133], v[68:69], v[132:133]
	v_pk_mul_f32 v[134:135], v[70:71], v[134:135]
	v_cvt_pk_bf16_f32 v132, v132, v133
	v_cvt_pk_bf16_f32 v133, v134, v135
	v_lshl_add_u64 v[182:183], v[182:183], 0, s[98:99]
	global_store_dwordx2 v[182:183], v[132:133], off
	v_pk_mul_f32 v[136:137], v[136:137], v[180:181] op_sel_hi:[1,0]
	v_pk_mul_f32 v[138:139], v[138:139], v[180:181] op_sel_hi:[1,0]
	v_pk_mul_f32 v[136:137], v[72:73], v[136:137]
	v_pk_mul_f32 v[138:139], v[74:75], v[138:139]
	v_cvt_pk_bf16_f32 v136, v136, v137
	v_cvt_pk_bf16_f32 v137, v138, v139
	v_lshl_add_u64 v[182:183], v[182:183], 0, s[98:99]
	global_store_dwordx2 v[182:183], v[136:137], off
	s_add_i32 s0, s101, s6
	s_add_i32 s101, s0, s6
	s_add_i32 s101, s101, s6
	s_cmp_lt_i32 s101, 0x8000
	s_cselect_b32 s8, s101, s100
	s_lshl_b32 s8, s8, 12
	s_mov_b32 s9, 0
	v_lshl_add_u64 v[184:185], v[2:3], 0, s[8:9]
	global_load_dwordx4 v[108:111], v[184:185], off
	global_load_dwordx4 v[112:115], v[184:185], off offset:1024
	global_load_dwordx4 v[116:119], v[184:185], off offset:2048
	global_load_dwordx4 v[120:123], v[184:185], off offset:3072
	s_add_i32 s1, s101, s6
	s_cmp_lt_i32 s1, 0x8000
	s_cselect_b32 s8, s1, s100
	s_lshl_b32 s8, s8, 12
	s_mov_b32 s9, 0
	v_lshl_add_u64 v[184:185], v[2:3], 0, s[8:9]
	global_load_dwordx4 v[124:127], v[184:185], off
	global_load_dwordx4 v[128:131], v[184:185], off offset:1024
	global_load_dwordx4 v[132:135], v[184:185], off offset:2048
	global_load_dwordx4 v[136:139], v[184:185], off offset:3072
	s_cmp_lt_i32 s0, 0x8000
	s_cbranch_scc0 .Lrms_done
	s_waitcnt vmcnt(16)
	v_mov_b32_e32 v142, v77
	v_mov_b32_e32 v143, v81
	v_mov_b32_e32 v140, v76
	v_mov_b32_e32 v141, v80
	v_mov_b32_e32 v150, v85
	v_mov_b32_e32 v151, v89
	v_pk_mul_f32 v[142:143], v[142:143], v[142:143]
	v_mov_b32_e32 v144, v78
	v_mov_b32_e32 v145, v82
	v_mov_b32_e32 v148, v84
	v_mov_b32_e32 v149, v88
	v_pk_mul_f32 v[150:151], v[150:151], v[150:151]
	v_pk_fma_f32 v[140:141], v[140:141], v[140:141], v[142:143]
	v_mov_b32_e32 v146, v79
	v_mov_b32_e32 v147, v83
	v_mov_b32_e32 v152, v86
	v_mov_b32_e32 v153, v90
	v_pk_fma_f32 v[142:143], v[148:149], v[148:149], v[150:151]
	v_pk_fma_f32 v[140:141], v[144:145], v[144:145], v[140:141]
	v_mov_b32_e32 v154, v87
	v_mov_b32_e32 v155, v91
	v_pk_fma_f32 v[142:143], v[152:153], v[152:153], v[142:143]
	v_pk_fma_f32 v[140:141], v[146:147], v[146:147], v[140:141]
	v_pk_fma_f32 v[142:143], v[154:155], v[154:155], v[142:143]
	v_add_f32_e32 v156, v140, v141
	v_add_f32_e32 v156, v156, v142
	v_add_f32_e32 v156, v156, v143
	v_mov_b32_e32 v164, v93
	v_mov_b32_e32 v165, v97
	v_mov_b32_e32 v162, v92
	v_mov_b32_e32 v163, v96
	v_mov_b32_e32 v172, v101
	v_mov_b32_e32 v173, v105
	v_pk_mul_f32 v[164:165], v[164:165], v[164:165]
	v_mov_b32_e32 v166, v94
	v_mov_b32_e32 v167, v98
	v_mov_b32_e32 v170, v100
	v_mov_b32_e32 v171, v104
	v_pk_mul_f32 v[172:173], v[172:173], v[172:173]
	v_pk_fma_f32 v[162:163], v[162:163], v[162:163], v[164:165]
	v_mov_b32_e32 v168, v95
	v_mov_b32_e32 v169, v99
	v_mov_b32_e32 v174, v102
	v_mov_b32_e32 v175, v106
	v_pk_fma_f32 v[164:165], v[170:171], v[170:171], v[172:173]
	v_pk_fma_f32 v[162:163], v[166:167], v[166:167], v[162:163]
	v_mov_b32_e32 v176, v103
	v_mov_b32_e32 v177, v107
	v_pk_fma_f32 v[164:165], v[174:175], v[174:175], v[164:165]
	v_pk_fma_f32 v[162:163], v[168:169], v[168:169], v[162:163]
	v_pk_fma_f32 v[164:165], v[176:177], v[176:177], v[164:165]
	v_add_f32_e32 v178, v162, v163
	v_add_f32_e32 v178, v178, v164
	v_add_f32_e32 v178, v178, v165
	ds_bpermute_b32 v157, v8, v156
	ds_bpermute_b32 v179, v8, v178
	s_waitcnt lgkmcnt(1)
	v_add_f32_e32 v156, v156, v157
	s_waitcnt lgkmcnt(0)
	v_add_f32_e32 v178, v178, v179
	ds_bpermute_b32 v157, v9, v156
	ds_bpermute_b32 v179, v9, v178
	s_waitcnt lgkmcnt(1)
	v_add_f32_e32 v156, v156, v157
	s_waitcnt lgkmcnt(0)
	v_add_f32_e32 v178, v178, v179
	ds_bpermute_b32 v157, v10, v156
	ds_bpermute_b32 v179, v10, v178
	s_waitcnt lgkmcnt(1)
	v_add_f32_e32 v156, v156, v157
	s_waitcnt lgkmcnt(0)
	v_add_f32_e32 v178, v178, v179
	ds_bpermute_b32 v157, v11, v156
	ds_bpermute_b32 v179, v11, v178
	s_waitcnt lgkmcnt(1)
	v_add_f32_e32 v156, v156, v157
	s_waitcnt lgkmcnt(0)
	v_add_f32_e32 v178, v178, v179
	ds_bpermute_b32 v157, v12, v156
	ds_bpermute_b32 v179, v12, v178
	s_waitcnt lgkmcnt(1)
	v_add_f32_e32 v156, v156, v157
	s_waitcnt lgkmcnt(0)
	v_add_f32_e32 v178, v178, v179
	ds_bpermute_b32 v157, v13, v156
	ds_bpermute_b32 v179, v13, v178
	s_waitcnt lgkmcnt(1)
	v_add_f32_e32 v156, v156, v157
	s_waitcnt lgkmcnt(0)
; DI unsigned pk2(float lo, float hi) { f32x2 v = {lo, hi}; bf16x2_t r = __builtin_convertvector(v, bf16x2_t); return __builtin_bit_cast(unsigned, r); }
; DI void phase_rmsnorm(const float* X, const float* g, bf16_t* H) {
;     ...
;         const float r = rsqrtf(ss * (1.f / DM) + 1e-6f);
; #pragma unroll
;         for (int i = 0; i < 4; ++i) {
;             const f32x4 gg = *(const f32x4*)(g + i * 256 + lane * 4);
;             u32x2 o2; o2[0] = pk2(v[i][0] * r * gg[0], v[i][1] * r * gg[1]); o2[1] = pk2(v[i][2] * r * gg[2], v[i][3] * r * gg[3]);
;             *(u32x2*)(H + (size_t)row * DM + i * 256 + lane * 4) = o2;
;         }
;     }
; __global__ void __launch_bounds__(256, 2) mega_kernel(Params p) {
;     ...
;     grid.sync();
	v_add_f32_e32 v178, v178, v179
	s_cmp_lt_i32 s0, 0x8000
	s_cselect_b32 s8, s0, s100
	s_lshl_b32 s8, s8, 6
	s_mov_b32 s9, 0
	v_fmamk_f32 v156, v156, 0x3a800000, v14
	v_mul_f32_e32 v157, 0x4b800000, v156
	v_cmp_gt_f32_e32 vcc, s7, v156
	s_nop 1
	v_cndmask_b32_e32 v156, v156, v157, vcc
	v_rsq_f32_e32 v156, v156
	v_lshl_add_u64 v[160:161], v[6:7], 0, s[8:9]
	v_mul_f32_e32 v158, 0x45800000, v156
	v_cndmask_b32_e32 v158, v156, v158, vcc
	v_pk_mul_f32 v[76:77], v[76:77], v[158:159] op_sel_hi:[1,0]
	v_pk_mul_f32 v[78:79], v[78:79], v[158:159] op_sel_hi:[1,0]
	v_pk_mul_f32 v[76:77], v[60:61], v[76:77]
	v_pk_mul_f32 v[78:79], v[62:63], v[78:79]
	v_cvt_pk_bf16_f32 v76, v76, v77
	v_cvt_pk_bf16_f32 v77, v78, v79
	global_store_dwordx2 v[160:161], v[76:77], off
	v_pk_mul_f32 v[80:81], v[80:81], v[158:159] op_sel_hi:[1,0]
	v_pk_mul_f32 v[82:83], v[82:83], v[158:159] op_sel_hi:[1,0]
	v_pk_mul_f32 v[80:81], v[64:65], v[80:81]
	v_pk_mul_f32 v[82:83], v[66:67], v[82:83]
	v_cvt_pk_bf16_f32 v80, v80, v81
	v_cvt_pk_bf16_f32 v81, v82, v83
	v_lshl_add_u64 v[160:161], v[160:161], 0, s[98:99]
	global_store_dwordx2 v[160:161], v[80:81], off
	v_pk_mul_f32 v[84:85], v[84:85], v[158:159] op_sel_hi:[1,0]
	v_pk_mul_f32 v[86:87], v[86:87], v[158:159] op_sel_hi:[1,0]
	v_pk_mul_f32 v[84:85], v[68:69], v[84:85]
	v_pk_mul_f32 v[86:87], v[70:71], v[86:87]
	v_cvt_pk_bf16_f32 v84, v84, v85
	v_cvt_pk_bf16_f32 v85, v86, v87
	v_lshl_add_u64 v[160:161], v[160:161], 0, s[98:99]
	global_store_dwordx2 v[160:161], v[84:85], off
	v_pk_mul_f32 v[88:89], v[88:89], v[158:159] op_sel_hi:[1,0]
	v_pk_mul_f32 v[90:91], v[90:91], v[158:159] op_sel_hi:[1,0]
	v_pk_mul_f32 v[88:89], v[72:73], v[88:89]
	v_pk_mul_f32 v[90:91], v[74:75], v[90:91]
	v_cvt_pk_bf16_f32 v88, v88, v89
	v_cvt_pk_bf16_f32 v89, v90, v91
	v_lshl_add_u64 v[160:161], v[160:161], 0, s[98:99]
	global_store_dwordx2 v[160:161], v[88:89], off
	s_add_i32 s101, s0, s6
	s_cmp_lt_i32 s101, 0x8000
	s_cselect_b32 s8, s101, s100
	s_lshl_b32 s8, s8, 6
	s_mov_b32 s9, 0
	v_fmamk_f32 v178, v178, 0x3a800000, v14
	v_mul_f32_e32 v179, 0x4b800000, v178
	v_cmp_gt_f32_e32 vcc, s7, v178
	s_nop 1
	v_cndmask_b32_e32 v178, v178, v179, vcc
	v_rsq_f32_e32 v178, v178
	v_lshl_add_u64 v[182:183], v[6:7], 0, s[8:9]
	v_mul_f32_e32 v180, 0x45800000, v178
	v_cndmask_b32_e32 v180, v178, v180, vcc
	v_pk_mul_f32 v[92:93], v[92:93], v[180:181] op_sel_hi:[1,0]
	v_pk_mul_f32 v[94:95], v[94:95], v[180:181] op_sel_hi:[1,0]
	v_pk_mul_f32 v[92:93], v[60:61], v[92:93]
	v_pk_mul_f32 v[94:95], v[62:63], v[94:95]
	v_cvt_pk_bf16_f32 v92, v92, v93
	v_cvt_pk_bf16_f32 v93, v94, v95
	global_store_dwordx2 v[182:183], v[92:93], off
	v_pk_mul_f32 v[96:97], v[96:97], v[180:181] op_sel_hi:[1,0]
	v_pk_mul_f32 v[98:99], v[98:99], v[180:181] op_sel_hi:[1,0]
	v_pk_mul_f32 v[96:97], v[64:65], v[96:97]
	v_pk_mul_f32 v[98:99], v[66:67], v[98:99]
	v_cvt_pk_bf16_f32 v96, v96, v97
	v_cvt_pk_bf16_f32 v97, v98, v99
	v_lshl_add_u64 v[182:183], v[182:183], 0, s[98:99]
	global_store_dwordx2 v[182:183], v[96:97], off
	v_pk_mul_f32 v[100:101], v[100:101], v[180:181] op_sel_hi:[1,0]
	v_pk_mul_f32 v[102:103], v[102:103], v[180:181] op_sel_hi:[1,0]
	v_pk_mul_f32 v[100:101], v[68:69], v[100:101]
	v_pk_mul_f32 v[102:103], v[70:71], v[102:103]
	v_cvt_pk_bf16_f32 v100, v100, v101
	v_cvt_pk_bf16_f32 v101, v102, v103
	v_lshl_add_u64 v[182:183], v[182:183], 0, s[98:99]
	global_store_dwordx2 v[182:183], v[100:101], off
	v_pk_mul_f32 v[104:105], v[104:105], v[180:181] op_sel_hi:[1,0]
	v_pk_mul_f32 v[106:107], v[106:107], v[180:181] op_sel_hi:[1,0]
	v_pk_mul_f32 v[104:105], v[72:73], v[104:105]
	v_pk_mul_f32 v[106:107], v[74:75], v[106:107]
	v_cvt_pk_bf16_f32 v104, v104, v105
	v_cvt_pk_bf16_f32 v105, v106, v107
	v_lshl_add_u64 v[182:183], v[182:183], 0, s[98:99]
	global_store_dwordx2 v[182:183], v[104:105], off
	s_add_i32 s0, s101, s6
	s_add_i32 s101, s0, s6
	s_add_i32 s101, s101, s6
	s_cmp_lt_i32 s101, 0x8000
	s_cselect_b32 s8, s101, s100
	s_lshl_b32 s8, s8, 12
	s_mov_b32 s9, 0
	v_lshl_add_u64 v[184:185], v[2:3], 0, s[8:9]
	global_load_dwordx4 v[76:79], v[184:185], off
	global_load_dwordx4 v[80:83], v[184:185], off offset:1024
	global_load_dwordx4 v[84:87], v[184:185], off offset:2048
	global_load_dwordx4 v[88:91], v[184:185], off offset:3072
	s_add_i32 s1, s101, s6
	s_cmp_lt_i32 s1, 0x8000
	s_cselect_b32 s8, s1, s100
	s_lshl_b32 s8, s8, 12
	s_mov_b32 s9, 0
	v_lshl_add_u64 v[184:185], v[2:3], 0, s[8:9]
	global_load_dwordx4 v[92:95], v[184:185], off
	global_load_dwordx4 v[96:99], v[184:185], off offset:1024
	global_load_dwordx4 v[100:103], v[184:185], off offset:2048
	global_load_dwordx4 v[104:107], v[184:185], off offset:3072
	s_branch .Lrms_loop
.Lrms_done:
	s_waitcnt vmcnt(0)
.LBB0_142:
	v_lshrrev_b32_e32 v2, 20, v0
	v_lshrrev_b32_e32 v0, 10, v0
	v_or_b32_e32 v0, v0, v2
	s_movk_i32 s0, 0x3ff
	v_and_or_b32 v0, v0, s0, v210
	v_cmp_eq_u32_e32 vcc, 0, v0
	s_barrier
	s_and_saveexec_b64 s[0:1], vcc
	s_cbranch_execz .LBB0_152
	buffer_wbl2 sc1
	s_waitcnt vmcnt(0)
	s_load_dwordx2 s[4:5], s[4:5], 0x58
	v_mov_b32_e32 v3, 0
	s_mov_b64 s[6:7], exec
	v_mbcnt_lo_u32_b32 v2, s6, 0
	v_mbcnt_hi_u32_b32 v2, s7, v2
	s_waitcnt lgkmcnt(0)
	global_load_dword v0, v3, s[4:5] offset:40
	v_cmp_eq_u32_e32 vcc, 0, v2
	s_and_saveexec_b64 s[8:9], vcc
	s_cbranch_execz .LBB0_145
	s_bcnt1_i32_b64 s6, s[6:7]
	v_mov_b32_e32 v4, s6
	global_atomic_add v4, v3, v4, s[4:5] offset:32 sc0
